# hyena filter: the 8 shifted copies written by an unrolled loop, 8 LDS reads in flight (was read-wait-write 64 times per thread)
# baseline (speedup 1.0000x reference)
; #define LAS __attribute__((address_space(3)))
; __device__ __forceinline__ unsigned pk2(float lo, float hi) { unsigned r; asm("v_cvt_pk_bf16_f32 %0, %1, %2" : "=v"(r) : "v"(lo), "v"(hi)); return r; }
; __device__ __forceinline__ void hy_filter(const Args& a, int L, int order, int c, LAS unsigned char* lds) {
;     ...
;     const float inv = 1.0f / tot;
;     for (int i = tid; i < 8 * 4096; i += 512) {
;         const int q = i >> 12, x = i & 4095;
;         const float v = tmp[(q - x) & 4095] * inv;
;         *(LAS bf16_t*)(lds + q * HY_CP + x * 2) = (bf16_t)(pk2(v, 0.f) & 0xffffu);
;     }
.LBB0_184:
	v_lshlrev_b32_e32 v6, 2, v3
	v_add_u32_e32 v4, 0x0, v6
	v_and_b32_e32 v4, 0x3ffc, v4
	v_add_u32_e32 v4, 0x10200, v4
	ds_read_b32 v8, v4
	v_add_u32_e32 v4, 0xfffff800, v6
	v_and_b32_e32 v4, 0x3ffc, v4
	v_add_u32_e32 v4, 0x10200, v4
	ds_read_b32 v9, v4
	v_add_u32_e32 v4, 0xfffff000, v6
	v_and_b32_e32 v4, 0x3ffc, v4
	v_add_u32_e32 v4, 0x10200, v4
	ds_read_b32 v10, v4
	v_add_u32_e32 v4, 0xffffe800, v6
	v_and_b32_e32 v4, 0x3ffc, v4
	v_add_u32_e32 v4, 0x10200, v4
	ds_read_b32 v11, v4
	v_add_u32_e32 v4, 0xffffe000, v6
	v_and_b32_e32 v4, 0x3ffc, v4
	v_add_u32_e32 v4, 0x10200, v4
	ds_read_b32 v12, v4
	v_add_u32_e32 v4, 0xffffd800, v6
	v_and_b32_e32 v4, 0x3ffc, v4
	v_add_u32_e32 v4, 0x10200, v4
	ds_read_b32 v13, v4
	v_add_u32_e32 v4, 0xffffd000, v6
	v_and_b32_e32 v4, 0x3ffc, v4
	v_add_u32_e32 v4, 0x10200, v4
	ds_read_b32 v14, v4
	v_add_u32_e32 v4, 0xffffc800, v6
	v_and_b32_e32 v4, 0x3ffc, v4
	v_add_u32_e32 v4, 0x10200, v4
	ds_read_b32 v15, v4
	v_add_u32_e32 v4, 0x4, v6
	v_and_b32_e32 v4, 0x3ffc, v4
	v_add_u32_e32 v4, 0x10200, v4
	ds_read_b32 v16, v4
	v_add_u32_e32 v4, 0xfffff804, v6
	v_and_b32_e32 v4, 0x3ffc, v4
	v_add_u32_e32 v4, 0x10200, v4
	ds_read_b32 v17, v4
	v_add_u32_e32 v4, 0xfffff004, v6
	v_and_b32_e32 v4, 0x3ffc, v4
	v_add_u32_e32 v4, 0x10200, v4
	ds_read_b32 v18, v4
	v_add_u32_e32 v4, 0xffffe804, v6
	v_and_b32_e32 v4, 0x3ffc, v4
	v_add_u32_e32 v4, 0x10200, v4
	ds_read_b32 v19, v4
	v_add_u32_e32 v4, 0xffffe004, v6
	v_and_b32_e32 v4, 0x3ffc, v4
	v_add_u32_e32 v4, 0x10200, v4
	ds_read_b32 v20, v4
	v_add_u32_e32 v4, 0xffffd804, v6
	v_and_b32_e32 v4, 0x3ffc, v4
	v_add_u32_e32 v4, 0x10200, v4
	ds_read_b32 v21, v4
	v_add_u32_e32 v4, 0xffffd004, v6
	v_and_b32_e32 v4, 0x3ffc, v4
	v_add_u32_e32 v4, 0x10200, v4
	ds_read_b32 v22, v4
	v_add_u32_e32 v4, 0xffffc804, v6
	v_and_b32_e32 v4, 0x3ffc, v4
	v_add_u32_e32 v4, 0x10200, v4
	ds_read_b32 v23, v4
	s_waitcnt lgkmcnt(8)
	v_mul_f32_e32 v8, v1, v8
	v_cvt_pk_bf16_f32 v8, v8, v155
	ds_write_b16 v2, v8 offset:0
	v_mul_f32_e32 v9, v1, v9
	v_cvt_pk_bf16_f32 v9, v9, v155
	ds_write_b16 v2, v9 offset:1024
	v_mul_f32_e32 v10, v1, v10
	v_cvt_pk_bf16_f32 v10, v10, v155
	ds_write_b16 v2, v10 offset:2048
	v_mul_f32_e32 v11, v1, v11
	v_cvt_pk_bf16_f32 v11, v11, v155
	ds_write_b16 v2, v11 offset:3072
	v_mul_f32_e32 v12, v1, v12
	v_cvt_pk_bf16_f32 v12, v12, v155
	ds_write_b16 v2, v12 offset:4096
	v_mul_f32_e32 v13, v1, v13
	v_cvt_pk_bf16_f32 v13, v13, v155
	ds_write_b16 v2, v13 offset:5120
	v_mul_f32_e32 v14, v1, v14
	v_cvt_pk_bf16_f32 v14, v14, v155
	ds_write_b16 v2, v14 offset:6144
	v_mul_f32_e32 v15, v1, v15
	v_cvt_pk_bf16_f32 v15, v15, v155
	ds_write_b16 v2, v15 offset:7168
	v_add_u32_e32 v4, 0x8, v6
	v_and_b32_e32 v4, 0x3ffc, v4
	v_add_u32_e32 v4, 0x10200, v4
	ds_read_b32 v8, v4
	v_add_u32_e32 v4, 0xfffff808, v6
	v_and_b32_e32 v4, 0x3ffc, v4
	v_add_u32_e32 v4, 0x10200, v4
	ds_read_b32 v9, v4
	v_add_u32_e32 v4, 0xfffff008, v6
	v_and_b32_e32 v4, 0x3ffc, v4
	v_add_u32_e32 v4, 0x10200, v4
	ds_read_b32 v10, v4
	v_add_u32_e32 v4, 0xffffe808, v6
	v_and_b32_e32 v4, 0x3ffc, v4
	v_add_u32_e32 v4, 0x10200, v4
	ds_read_b32 v11, v4
	v_add_u32_e32 v4, 0xffffe008, v6
	v_and_b32_e32 v4, 0x3ffc, v4
	v_add_u32_e32 v4, 0x10200, v4
	ds_read_b32 v12, v4
	v_add_u32_e32 v4, 0xffffd808, v6
	v_and_b32_e32 v4, 0x3ffc, v4
	v_add_u32_e32 v4, 0x10200, v4
	ds_read_b32 v13, v4
	v_add_u32_e32 v4, 0xffffd008, v6
	v_and_b32_e32 v4, 0x3ffc, v4
	v_add_u32_e32 v4, 0x10200, v4
	ds_read_b32 v14, v4
	v_add_u32_e32 v4, 0xffffc808, v6
	v_and_b32_e32 v4, 0x3ffc, v4
	v_add_u32_e32 v4, 0x10200, v4
	ds_read_b32 v15, v4
	s_waitcnt lgkmcnt(8)
	v_mul_f32_e32 v16, v1, v16
	v_cvt_pk_bf16_f32 v16, v16, v155
	ds_write_b16 v2, v16 offset:8256
	v_mul_f32_e32 v17, v1, v17
	v_cvt_pk_bf16_f32 v17, v17, v155
	ds_write_b16 v2, v17 offset:9280
	v_mul_f32_e32 v18, v1, v18
	v_cvt_pk_bf16_f32 v18, v18, v155
	ds_write_b16 v2, v18 offset:10304
	v_mul_f32_e32 v19, v1, v19
	v_cvt_pk_bf16_f32 v19, v19, v155
	ds_write_b16 v2, v19 offset:11328
	v_mul_f32_e32 v20, v1, v20
	v_cvt_pk_bf16_f32 v20, v20, v155
	ds_write_b16 v2, v20 offset:12352
	v_mul_f32_e32 v21, v1, v21
	v_cvt_pk_bf16_f32 v21, v21, v155
	ds_write_b16 v2, v21 offset:13376
	v_mul_f32_e32 v22, v1, v22
	v_cvt_pk_bf16_f32 v22, v22, v155
	ds_write_b16 v2, v22 offset:14400
	v_mul_f32_e32 v23, v1, v23
	v_cvt_pk_bf16_f32 v23, v23, v155
	ds_write_b16 v2, v23 offset:15424
	v_add_u32_e32 v4, 0xc, v6
	v_and_b32_e32 v4, 0x3ffc, v4
	v_add_u32_e32 v4, 0x10200, v4
	ds_read_b32 v16, v4
	v_add_u32_e32 v4, 0xfffff80c, v6
	v_and_b32_e32 v4, 0x3ffc, v4
	v_add_u32_e32 v4, 0x10200, v4
	ds_read_b32 v17, v4
	v_add_u32_e32 v4, 0xfffff00c, v6
	v_and_b32_e32 v4, 0x3ffc, v4
	v_add_u32_e32 v4, 0x10200, v4
	ds_read_b32 v18, v4
	v_add_u32_e32 v4, 0xffffe80c, v6
	v_and_b32_e32 v4, 0x3ffc, v4
	v_add_u32_e32 v4, 0x10200, v4
	ds_read_b32 v19, v4
	v_add_u32_e32 v4, 0xffffe00c, v6
	v_and_b32_e32 v4, 0x3ffc, v4
	v_add_u32_e32 v4, 0x10200, v4
	ds_read_b32 v20, v4
	v_add_u32_e32 v4, 0xffffd80c, v6
	v_and_b32_e32 v4, 0x3ffc, v4
	v_add_u32_e32 v4, 0x10200, v4
	ds_read_b32 v21, v4
	v_add_u32_e32 v4, 0xffffd00c, v6
	v_and_b32_e32 v4, 0x3ffc, v4
	v_add_u32_e32 v4, 0x10200, v4
	ds_read_b32 v22, v4
	v_add_u32_e32 v4, 0xffffc80c, v6
	v_and_b32_e32 v4, 0x3ffc, v4
	v_add_u32_e32 v4, 0x10200, v4
	ds_read_b32 v23, v4
	s_waitcnt lgkmcnt(8)
; #define LAS __attribute__((address_space(3)))
; __device__ __forceinline__ unsigned pk2(float lo, float hi) { unsigned r; asm("v_cvt_pk_bf16_f32 %0, %1, %2" : "=v"(r) : "v"(lo), "v"(hi)); return r; }
; __device__ __forceinline__ void hy_filter(const Args& a, int L, int order, int c, LAS unsigned char* lds) {
;     ...
;     const float inv = 1.0f / tot;
;     for (int i = tid; i < 8 * 4096; i += 512) {
;         const int q = i >> 12, x = i & 4095;
;         const float v = tmp[(q - x) & 4095] * inv;
;         *(LAS bf16_t*)(lds + q * HY_CP + x * 2) = (bf16_t)(pk2(v, 0.f) & 0xffffu);
;     }
	v_mul_f32_e32 v8, v1, v8
	v_cvt_pk_bf16_f32 v8, v8, v155
	ds_write_b16 v2, v8 offset:16512
	v_mul_f32_e32 v9, v1, v9
	v_cvt_pk_bf16_f32 v9, v9, v155
	ds_write_b16 v2, v9 offset:17536
	v_mul_f32_e32 v10, v1, v10
	v_cvt_pk_bf16_f32 v10, v10, v155
	ds_write_b16 v2, v10 offset:18560
	v_mul_f32_e32 v11, v1, v11
	v_cvt_pk_bf16_f32 v11, v11, v155
	ds_write_b16 v2, v11 offset:19584
	v_mul_f32_e32 v12, v1, v12
	v_cvt_pk_bf16_f32 v12, v12, v155
	ds_write_b16 v2, v12 offset:20608
	v_mul_f32_e32 v13, v1, v13
	v_cvt_pk_bf16_f32 v13, v13, v155
	ds_write_b16 v2, v13 offset:21632
	v_mul_f32_e32 v14, v1, v14
	v_cvt_pk_bf16_f32 v14, v14, v155
	ds_write_b16 v2, v14 offset:22656
	v_mul_f32_e32 v15, v1, v15
	v_cvt_pk_bf16_f32 v15, v15, v155
	ds_write_b16 v2, v15 offset:23680
	v_add_u32_e32 v4, 0x10, v6
	v_and_b32_e32 v4, 0x3ffc, v4
	v_add_u32_e32 v4, 0x10200, v4
	ds_read_b32 v8, v4
	v_add_u32_e32 v4, 0xfffff810, v6
	v_and_b32_e32 v4, 0x3ffc, v4
	v_add_u32_e32 v4, 0x10200, v4
	ds_read_b32 v9, v4
	v_add_u32_e32 v4, 0xfffff010, v6
	v_and_b32_e32 v4, 0x3ffc, v4
	v_add_u32_e32 v4, 0x10200, v4
	ds_read_b32 v10, v4
	v_add_u32_e32 v4, 0xffffe810, v6
	v_and_b32_e32 v4, 0x3ffc, v4
	v_add_u32_e32 v4, 0x10200, v4
	ds_read_b32 v11, v4
	v_add_u32_e32 v4, 0xffffe010, v6
	v_and_b32_e32 v4, 0x3ffc, v4
	v_add_u32_e32 v4, 0x10200, v4
	ds_read_b32 v12, v4
	v_add_u32_e32 v4, 0xffffd810, v6
	v_and_b32_e32 v4, 0x3ffc, v4
	v_add_u32_e32 v4, 0x10200, v4
	ds_read_b32 v13, v4
	v_add_u32_e32 v4, 0xffffd010, v6
	v_and_b32_e32 v4, 0x3ffc, v4
	v_add_u32_e32 v4, 0x10200, v4
	ds_read_b32 v14, v4
	v_add_u32_e32 v4, 0xffffc810, v6
	v_and_b32_e32 v4, 0x3ffc, v4
	v_add_u32_e32 v4, 0x10200, v4
	ds_read_b32 v15, v4
	s_waitcnt lgkmcnt(8)
	v_mul_f32_e32 v16, v1, v16
	v_cvt_pk_bf16_f32 v16, v16, v155
	ds_write_b16 v2, v16 offset:24768
	v_mul_f32_e32 v17, v1, v17
	v_cvt_pk_bf16_f32 v17, v17, v155
	ds_write_b16 v2, v17 offset:25792
	v_mul_f32_e32 v18, v1, v18
	v_cvt_pk_bf16_f32 v18, v18, v155
	ds_write_b16 v2, v18 offset:26816
	v_mul_f32_e32 v19, v1, v19
	v_cvt_pk_bf16_f32 v19, v19, v155
	ds_write_b16 v2, v19 offset:27840
	v_mul_f32_e32 v20, v1, v20
	v_cvt_pk_bf16_f32 v20, v20, v155
	ds_write_b16 v2, v20 offset:28864
	v_mul_f32_e32 v21, v1, v21
	v_cvt_pk_bf16_f32 v21, v21, v155
	ds_write_b16 v2, v21 offset:29888
	v_mul_f32_e32 v22, v1, v22
	v_cvt_pk_bf16_f32 v22, v22, v155
	ds_write_b16 v2, v22 offset:30912
	v_mul_f32_e32 v23, v1, v23
	v_cvt_pk_bf16_f32 v23, v23, v155
	ds_write_b16 v2, v23 offset:31936
	v_add_u32_e32 v4, 0x14, v6
	v_and_b32_e32 v4, 0x3ffc, v4
	v_add_u32_e32 v4, 0x10200, v4
	ds_read_b32 v16, v4
	v_add_u32_e32 v4, 0xfffff814, v6
	v_and_b32_e32 v4, 0x3ffc, v4
	v_add_u32_e32 v4, 0x10200, v4
	ds_read_b32 v17, v4
	v_add_u32_e32 v4, 0xfffff014, v6
	v_and_b32_e32 v4, 0x3ffc, v4
	v_add_u32_e32 v4, 0x10200, v4
	ds_read_b32 v18, v4
	v_add_u32_e32 v4, 0xffffe814, v6
	v_and_b32_e32 v4, 0x3ffc, v4
	v_add_u32_e32 v4, 0x10200, v4
	ds_read_b32 v19, v4
	v_add_u32_e32 v4, 0xffffe014, v6
	v_and_b32_e32 v4, 0x3ffc, v4
	v_add_u32_e32 v4, 0x10200, v4
	ds_read_b32 v20, v4
	v_add_u32_e32 v4, 0xffffd814, v6
	v_and_b32_e32 v4, 0x3ffc, v4
	v_add_u32_e32 v4, 0x10200, v4
	ds_read_b32 v21, v4
	v_add_u32_e32 v4, 0xffffd014, v6
	v_and_b32_e32 v4, 0x3ffc, v4
	v_add_u32_e32 v4, 0x10200, v4
	ds_read_b32 v22, v4
	v_add_u32_e32 v4, 0xffffc814, v6
	v_and_b32_e32 v4, 0x3ffc, v4
	v_add_u32_e32 v4, 0x10200, v4
	ds_read_b32 v23, v4
	s_waitcnt lgkmcnt(8)
; #define LAS __attribute__((address_space(3)))
; __device__ __forceinline__ unsigned pk2(float lo, float hi) { unsigned r; asm("v_cvt_pk_bf16_f32 %0, %1, %2" : "=v"(r) : "v"(lo), "v"(hi)); return r; }
; __device__ __forceinline__ void hy_filter(const Args& a, int L, int order, int c, LAS unsigned char* lds) {
;     ...
;     const float inv = 1.0f / tot;
;     for (int i = tid; i < 8 * 4096; i += 512) {
;         const int q = i >> 12, x = i & 4095;
;         const float v = tmp[(q - x) & 4095] * inv;
;         *(LAS bf16_t*)(lds + q * HY_CP + x * 2) = (bf16_t)(pk2(v, 0.f) & 0xffffu);
;     }
	v_mul_f32_e32 v8, v1, v8
	v_cvt_pk_bf16_f32 v8, v8, v155
	ds_write_b16 v2, v8 offset:33024
	v_mul_f32_e32 v9, v1, v9
	v_cvt_pk_bf16_f32 v9, v9, v155
	ds_write_b16 v2, v9 offset:34048
	v_mul_f32_e32 v10, v1, v10
	v_cvt_pk_bf16_f32 v10, v10, v155
	ds_write_b16 v2, v10 offset:35072
	v_mul_f32_e32 v11, v1, v11
	v_cvt_pk_bf16_f32 v11, v11, v155
	ds_write_b16 v2, v11 offset:36096
	v_mul_f32_e32 v12, v1, v12
	v_cvt_pk_bf16_f32 v12, v12, v155
	ds_write_b16 v2, v12 offset:37120
	v_mul_f32_e32 v13, v1, v13
	v_cvt_pk_bf16_f32 v13, v13, v155
	ds_write_b16 v2, v13 offset:38144
	v_mul_f32_e32 v14, v1, v14
	v_cvt_pk_bf16_f32 v14, v14, v155
	ds_write_b16 v2, v14 offset:39168
	v_mul_f32_e32 v15, v1, v15
	v_cvt_pk_bf16_f32 v15, v15, v155
	ds_write_b16 v2, v15 offset:40192
	v_add_u32_e32 v4, 0x18, v6
	v_and_b32_e32 v4, 0x3ffc, v4
	v_add_u32_e32 v4, 0x10200, v4
	ds_read_b32 v8, v4
	v_add_u32_e32 v4, 0xfffff818, v6
	v_and_b32_e32 v4, 0x3ffc, v4
	v_add_u32_e32 v4, 0x10200, v4
	ds_read_b32 v9, v4
	v_add_u32_e32 v4, 0xfffff018, v6
	v_and_b32_e32 v4, 0x3ffc, v4
	v_add_u32_e32 v4, 0x10200, v4
	ds_read_b32 v10, v4
	v_add_u32_e32 v4, 0xffffe818, v6
	v_and_b32_e32 v4, 0x3ffc, v4
	v_add_u32_e32 v4, 0x10200, v4
	ds_read_b32 v11, v4
	v_add_u32_e32 v4, 0xffffe018, v6
	v_and_b32_e32 v4, 0x3ffc, v4
	v_add_u32_e32 v4, 0x10200, v4
	ds_read_b32 v12, v4
	v_add_u32_e32 v4, 0xffffd818, v6
	v_and_b32_e32 v4, 0x3ffc, v4
	v_add_u32_e32 v4, 0x10200, v4
	ds_read_b32 v13, v4
	v_add_u32_e32 v4, 0xffffd018, v6
	v_and_b32_e32 v4, 0x3ffc, v4
	v_add_u32_e32 v4, 0x10200, v4
	ds_read_b32 v14, v4
	v_add_u32_e32 v4, 0xffffc818, v6
	v_and_b32_e32 v4, 0x3ffc, v4
	v_add_u32_e32 v4, 0x10200, v4
	ds_read_b32 v15, v4
	s_waitcnt lgkmcnt(8)
	v_mul_f32_e32 v16, v1, v16
	v_cvt_pk_bf16_f32 v16, v16, v155
	ds_write_b16 v2, v16 offset:41280
	v_mul_f32_e32 v17, v1, v17
	v_cvt_pk_bf16_f32 v17, v17, v155
	ds_write_b16 v2, v17 offset:42304
	v_mul_f32_e32 v18, v1, v18
	v_cvt_pk_bf16_f32 v18, v18, v155
	ds_write_b16 v2, v18 offset:43328
	v_mul_f32_e32 v19, v1, v19
	v_cvt_pk_bf16_f32 v19, v19, v155
	ds_write_b16 v2, v19 offset:44352
	v_mul_f32_e32 v20, v1, v20
	v_cvt_pk_bf16_f32 v20, v20, v155
	ds_write_b16 v2, v20 offset:45376
	v_mul_f32_e32 v21, v1, v21
	v_cvt_pk_bf16_f32 v21, v21, v155
	ds_write_b16 v2, v21 offset:46400
	v_mul_f32_e32 v22, v1, v22
	v_cvt_pk_bf16_f32 v22, v22, v155
	ds_write_b16 v2, v22 offset:47424
	v_mul_f32_e32 v23, v1, v23
	v_cvt_pk_bf16_f32 v23, v23, v155
	ds_write_b16 v2, v23 offset:48448
	v_add_u32_e32 v4, 0x1c, v6
	v_and_b32_e32 v4, 0x3ffc, v4
	v_add_u32_e32 v4, 0x10200, v4
	ds_read_b32 v16, v4
	v_add_u32_e32 v4, 0xfffff81c, v6
	v_and_b32_e32 v4, 0x3ffc, v4
	v_add_u32_e32 v4, 0x10200, v4
	ds_read_b32 v17, v4
	v_add_u32_e32 v4, 0xfffff01c, v6
	v_and_b32_e32 v4, 0x3ffc, v4
	v_add_u32_e32 v4, 0x10200, v4
	ds_read_b32 v18, v4
	v_add_u32_e32 v4, 0xffffe81c, v6
	v_and_b32_e32 v4, 0x3ffc, v4
	v_add_u32_e32 v4, 0x10200, v4
	ds_read_b32 v19, v4
	v_add_u32_e32 v4, 0xffffe01c, v6
	v_and_b32_e32 v4, 0x3ffc, v4
	v_add_u32_e32 v4, 0x10200, v4
	ds_read_b32 v20, v4
	v_add_u32_e32 v4, 0xffffd81c, v6
	v_and_b32_e32 v4, 0x3ffc, v4
	v_add_u32_e32 v4, 0x10200, v4
	ds_read_b32 v21, v4
	v_add_u32_e32 v4, 0xffffd01c, v6
	v_and_b32_e32 v4, 0x3ffc, v4
	v_add_u32_e32 v4, 0x10200, v4
	ds_read_b32 v22, v4
	v_add_u32_e32 v4, 0xffffc81c, v6
	v_and_b32_e32 v4, 0x3ffc, v4
	v_add_u32_e32 v4, 0x10200, v4
	ds_read_b32 v23, v4
	s_waitcnt lgkmcnt(8)
	v_mul_f32_e32 v8, v1, v8
	v_cvt_pk_bf16_f32 v8, v8, v155
	ds_write_b16 v2, v8 offset:49536
	v_mul_f32_e32 v9, v1, v9
	v_cvt_pk_bf16_f32 v9, v9, v155
	ds_write_b16 v2, v9 offset:50560
	v_mul_f32_e32 v10, v1, v10
	v_cvt_pk_bf16_f32 v10, v10, v155
	ds_write_b16 v2, v10 offset:51584
	v_mul_f32_e32 v11, v1, v11
	v_cvt_pk_bf16_f32 v11, v11, v155
	ds_write_b16 v2, v11 offset:52608
	v_mul_f32_e32 v12, v1, v12
	v_cvt_pk_bf16_f32 v12, v12, v155
	ds_write_b16 v2, v12 offset:53632
	v_mul_f32_e32 v13, v1, v13
	v_cvt_pk_bf16_f32 v13, v13, v155
	ds_write_b16 v2, v13 offset:54656
	v_mul_f32_e32 v14, v1, v14
	v_cvt_pk_bf16_f32 v14, v14, v155
	ds_write_b16 v2, v14 offset:55680
	v_mul_f32_e32 v15, v1, v15
	v_cvt_pk_bf16_f32 v15, v15, v155
	ds_write_b16 v2, v15 offset:56704
	s_waitcnt lgkmcnt(0)
	v_mul_f32_e32 v16, v1, v16
	v_cvt_pk_bf16_f32 v16, v16, v155
	ds_write_b16 v2, v16 offset:57792
	v_mul_f32_e32 v17, v1, v17
	v_cvt_pk_bf16_f32 v17, v17, v155
	ds_write_b16 v2, v17 offset:58816
	v_mul_f32_e32 v18, v1, v18
	v_cvt_pk_bf16_f32 v18, v18, v155
	ds_write_b16 v2, v18 offset:59840
	v_mul_f32_e32 v19, v1, v19
	v_cvt_pk_bf16_f32 v19, v19, v155
	ds_write_b16 v2, v19 offset:60864
	v_mul_f32_e32 v20, v1, v20
	v_cvt_pk_bf16_f32 v20, v20, v155
	ds_write_b16 v2, v20 offset:61888
	v_mul_f32_e32 v21, v1, v21
	v_cvt_pk_bf16_f32 v21, v21, v155
	ds_write_b16 v2, v21 offset:62912
	v_mul_f32_e32 v22, v1, v22
	v_cvt_pk_bf16_f32 v22, v22, v155
	ds_write_b16 v2, v22 offset:63936
	v_mul_f32_e32 v23, v1, v23
	v_cvt_pk_bf16_f32 v23, v23, v155
	ds_write_b16 v2, v23 offset:64960
	v_add_u32_e32 v0, 0x8000, v0
	v_add_u32_e32 v2, 0x10000, v2
	v_add_u32_e32 v3, 0xffff8000, v3
	s_mov_b64 s[2:3], exec

; #define LAS __attribute__((address_space(3)))
; __device__ __forceinline__ unsigned pk2(float lo, float hi) { unsigned r; asm("v_cvt_pk_bf16_f32 %0, %1, %2" : "=v"(r) : "v"(lo), "v"(hi)); return r; }
; __device__ __forceinline__ void hy_filter(const Args& a, int L, int order, int c, LAS unsigned char* lds) {
;     ...
;     const float inv = 1.0f / tot;
;     for (int i = tid; i < 8 * 4096; i += 512) {
;         const int q = i >> 12, x = i & 4095;
;         const float v = tmp[(q - x) & 4095] * inv;
;         *(LAS bf16_t*)(lds + q * HY_CP + x * 2) = (bf16_t)(pk2(v, 0.f) & 0xffffu);
;     }
.LBB0_205:
	v_lshlrev_b32_e32 v6, 2, v3
	v_add_u32_e32 v4, 0x0, v6
	v_and_b32_e32 v4, 0x3ffc, v4
	v_add_u32_e32 v4, 0x10200, v4
	ds_read_b32 v8, v4
	v_add_u32_e32 v4, 0xfffff800, v6
	v_and_b32_e32 v4, 0x3ffc, v4
	v_add_u32_e32 v4, 0x10200, v4
	ds_read_b32 v9, v4
	v_add_u32_e32 v4, 0xfffff000, v6
	v_and_b32_e32 v4, 0x3ffc, v4
	v_add_u32_e32 v4, 0x10200, v4
	ds_read_b32 v10, v4
	v_add_u32_e32 v4, 0xffffe800, v6
	v_and_b32_e32 v4, 0x3ffc, v4
	v_add_u32_e32 v4, 0x10200, v4
	ds_read_b32 v11, v4
	v_add_u32_e32 v4, 0xffffe000, v6
	v_and_b32_e32 v4, 0x3ffc, v4
	v_add_u32_e32 v4, 0x10200, v4
	ds_read_b32 v12, v4
	v_add_u32_e32 v4, 0xffffd800, v6
	v_and_b32_e32 v4, 0x3ffc, v4
	v_add_u32_e32 v4, 0x10200, v4
	ds_read_b32 v13, v4
	v_add_u32_e32 v4, 0xffffd000, v6
	v_and_b32_e32 v4, 0x3ffc, v4
	v_add_u32_e32 v4, 0x10200, v4
	ds_read_b32 v14, v4
	v_add_u32_e32 v4, 0xffffc800, v6
	v_and_b32_e32 v4, 0x3ffc, v4
	v_add_u32_e32 v4, 0x10200, v4
	ds_read_b32 v15, v4
	v_add_u32_e32 v4, 0x4, v6
	v_and_b32_e32 v4, 0x3ffc, v4
	v_add_u32_e32 v4, 0x10200, v4
	ds_read_b32 v16, v4
	v_add_u32_e32 v4, 0xfffff804, v6
	v_and_b32_e32 v4, 0x3ffc, v4
	v_add_u32_e32 v4, 0x10200, v4
	ds_read_b32 v17, v4
	v_add_u32_e32 v4, 0xfffff004, v6
	v_and_b32_e32 v4, 0x3ffc, v4
	v_add_u32_e32 v4, 0x10200, v4
	ds_read_b32 v18, v4
	v_add_u32_e32 v4, 0xffffe804, v6
	v_and_b32_e32 v4, 0x3ffc, v4
	v_add_u32_e32 v4, 0x10200, v4
	ds_read_b32 v19, v4
	v_add_u32_e32 v4, 0xffffe004, v6
	v_and_b32_e32 v4, 0x3ffc, v4
	v_add_u32_e32 v4, 0x10200, v4
	ds_read_b32 v20, v4
	v_add_u32_e32 v4, 0xffffd804, v6
	v_and_b32_e32 v4, 0x3ffc, v4
	v_add_u32_e32 v4, 0x10200, v4
	ds_read_b32 v21, v4
	v_add_u32_e32 v4, 0xffffd004, v6
	v_and_b32_e32 v4, 0x3ffc, v4
	v_add_u32_e32 v4, 0x10200, v4
	ds_read_b32 v22, v4
	v_add_u32_e32 v4, 0xffffc804, v6
	v_and_b32_e32 v4, 0x3ffc, v4
	v_add_u32_e32 v4, 0x10200, v4
	ds_read_b32 v23, v4
	s_waitcnt lgkmcnt(8)
	v_mul_f32_e32 v8, v1, v8
	v_cvt_pk_bf16_f32 v8, v8, v155
	ds_write_b16 v2, v8 offset:0
	v_mul_f32_e32 v9, v1, v9
	v_cvt_pk_bf16_f32 v9, v9, v155
	ds_write_b16 v2, v9 offset:1024
	v_mul_f32_e32 v10, v1, v10
	v_cvt_pk_bf16_f32 v10, v10, v155
	ds_write_b16 v2, v10 offset:2048
	v_mul_f32_e32 v11, v1, v11
	v_cvt_pk_bf16_f32 v11, v11, v155
	ds_write_b16 v2, v11 offset:3072
	v_mul_f32_e32 v12, v1, v12
	v_cvt_pk_bf16_f32 v12, v12, v155
	ds_write_b16 v2, v12 offset:4096
	v_mul_f32_e32 v13, v1, v13
	v_cvt_pk_bf16_f32 v13, v13, v155
	ds_write_b16 v2, v13 offset:5120
	v_mul_f32_e32 v14, v1, v14
	v_cvt_pk_bf16_f32 v14, v14, v155
	ds_write_b16 v2, v14 offset:6144
	v_mul_f32_e32 v15, v1, v15
	v_cvt_pk_bf16_f32 v15, v15, v155
	ds_write_b16 v2, v15 offset:7168
	v_add_u32_e32 v4, 0x8, v6
	v_and_b32_e32 v4, 0x3ffc, v4
	v_add_u32_e32 v4, 0x10200, v4
	ds_read_b32 v8, v4
	v_add_u32_e32 v4, 0xfffff808, v6
	v_and_b32_e32 v4, 0x3ffc, v4
	v_add_u32_e32 v4, 0x10200, v4
	ds_read_b32 v9, v4
	v_add_u32_e32 v4, 0xfffff008, v6
	v_and_b32_e32 v4, 0x3ffc, v4
	v_add_u32_e32 v4, 0x10200, v4
	ds_read_b32 v10, v4
	v_add_u32_e32 v4, 0xffffe808, v6
	v_and_b32_e32 v4, 0x3ffc, v4
	v_add_u32_e32 v4, 0x10200, v4
	ds_read_b32 v11, v4
	v_add_u32_e32 v4, 0xffffe008, v6
	v_and_b32_e32 v4, 0x3ffc, v4
	v_add_u32_e32 v4, 0x10200, v4
	ds_read_b32 v12, v4
	v_add_u32_e32 v4, 0xffffd808, v6
	v_and_b32_e32 v4, 0x3ffc, v4
	v_add_u32_e32 v4, 0x10200, v4
	ds_read_b32 v13, v4
	v_add_u32_e32 v4, 0xffffd008, v6
	v_and_b32_e32 v4, 0x3ffc, v4
	v_add_u32_e32 v4, 0x10200, v4
	ds_read_b32 v14, v4
	v_add_u32_e32 v4, 0xffffc808, v6
	v_and_b32_e32 v4, 0x3ffc, v4
	v_add_u32_e32 v4, 0x10200, v4
	ds_read_b32 v15, v4
	s_waitcnt lgkmcnt(8)
	v_mul_f32_e32 v16, v1, v16
	v_cvt_pk_bf16_f32 v16, v16, v155
	ds_write_b16 v2, v16 offset:8256
	v_mul_f32_e32 v17, v1, v17
	v_cvt_pk_bf16_f32 v17, v17, v155
	ds_write_b16 v2, v17 offset:9280
	v_mul_f32_e32 v18, v1, v18
	v_cvt_pk_bf16_f32 v18, v18, v155
	ds_write_b16 v2, v18 offset:10304
	v_mul_f32_e32 v19, v1, v19
	v_cvt_pk_bf16_f32 v19, v19, v155
	ds_write_b16 v2, v19 offset:11328
	v_mul_f32_e32 v20, v1, v20
	v_cvt_pk_bf16_f32 v20, v20, v155
	ds_write_b16 v2, v20 offset:12352
	v_mul_f32_e32 v21, v1, v21
	v_cvt_pk_bf16_f32 v21, v21, v155
	ds_write_b16 v2, v21 offset:13376
	v_mul_f32_e32 v22, v1, v22
	v_cvt_pk_bf16_f32 v22, v22, v155
	ds_write_b16 v2, v22 offset:14400
	v_mul_f32_e32 v23, v1, v23
	v_cvt_pk_bf16_f32 v23, v23, v155
	ds_write_b16 v2, v23 offset:15424
	v_add_u32_e32 v4, 0xc, v6
	v_and_b32_e32 v4, 0x3ffc, v4
	v_add_u32_e32 v4, 0x10200, v4
	ds_read_b32 v16, v4
	v_add_u32_e32 v4, 0xfffff80c, v6
	v_and_b32_e32 v4, 0x3ffc, v4
	v_add_u32_e32 v4, 0x10200, v4
	ds_read_b32 v17, v4
	v_add_u32_e32 v4, 0xfffff00c, v6
	v_and_b32_e32 v4, 0x3ffc, v4
	v_add_u32_e32 v4, 0x10200, v4
	ds_read_b32 v18, v4
	v_add_u32_e32 v4, 0xffffe80c, v6
	v_and_b32_e32 v4, 0x3ffc, v4
	v_add_u32_e32 v4, 0x10200, v4
	ds_read_b32 v19, v4
	v_add_u32_e32 v4, 0xffffe00c, v6
	v_and_b32_e32 v4, 0x3ffc, v4
	v_add_u32_e32 v4, 0x10200, v4
	ds_read_b32 v20, v4
	v_add_u32_e32 v4, 0xffffd80c, v6
	v_and_b32_e32 v4, 0x3ffc, v4
	v_add_u32_e32 v4, 0x10200, v4
	ds_read_b32 v21, v4
	v_add_u32_e32 v4, 0xffffd00c, v6
	v_and_b32_e32 v4, 0x3ffc, v4
	v_add_u32_e32 v4, 0x10200, v4
	ds_read_b32 v22, v4
	v_add_u32_e32 v4, 0xffffc80c, v6
	v_and_b32_e32 v4, 0x3ffc, v4
	v_add_u32_e32 v4, 0x10200, v4
	ds_read_b32 v23, v4
	s_waitcnt lgkmcnt(8)
; #define LAS __attribute__((address_space(3)))
; __device__ __forceinline__ unsigned pk2(float lo, float hi) { unsigned r; asm("v_cvt_pk_bf16_f32 %0, %1, %2" : "=v"(r) : "v"(lo), "v"(hi)); return r; }
; __device__ __forceinline__ void hy_filter(const Args& a, int L, int order, int c, LAS unsigned char* lds) {
;     ...
;     const float inv = 1.0f / tot;
;     for (int i = tid; i < 8 * 4096; i += 512) {
;         const int q = i >> 12, x = i & 4095;
;         const float v = tmp[(q - x) & 4095] * inv;
;         *(LAS bf16_t*)(lds + q * HY_CP + x * 2) = (bf16_t)(pk2(v, 0.f) & 0xffffu);
;     }
	v_mul_f32_e32 v8, v1, v8
	v_cvt_pk_bf16_f32 v8, v8, v155
	ds_write_b16 v2, v8 offset:16512
	v_mul_f32_e32 v9, v1, v9
	v_cvt_pk_bf16_f32 v9, v9, v155
	ds_write_b16 v2, v9 offset:17536
	v_mul_f32_e32 v10, v1, v10
	v_cvt_pk_bf16_f32 v10, v10, v155
	ds_write_b16 v2, v10 offset:18560
	v_mul_f32_e32 v11, v1, v11
	v_cvt_pk_bf16_f32 v11, v11, v155
	ds_write_b16 v2, v11 offset:19584
	v_mul_f32_e32 v12, v1, v12
	v_cvt_pk_bf16_f32 v12, v12, v155
	ds_write_b16 v2, v12 offset:20608
	v_mul_f32_e32 v13, v1, v13
	v_cvt_pk_bf16_f32 v13, v13, v155
	ds_write_b16 v2, v13 offset:21632
	v_mul_f32_e32 v14, v1, v14
	v_cvt_pk_bf16_f32 v14, v14, v155
	ds_write_b16 v2, v14 offset:22656
	v_mul_f32_e32 v15, v1, v15
	v_cvt_pk_bf16_f32 v15, v15, v155
	ds_write_b16 v2, v15 offset:23680
	v_add_u32_e32 v4, 0x10, v6
	v_and_b32_e32 v4, 0x3ffc, v4
	v_add_u32_e32 v4, 0x10200, v4
	ds_read_b32 v8, v4
	v_add_u32_e32 v4, 0xfffff810, v6
	v_and_b32_e32 v4, 0x3ffc, v4
	v_add_u32_e32 v4, 0x10200, v4
	ds_read_b32 v9, v4
	v_add_u32_e32 v4, 0xfffff010, v6
	v_and_b32_e32 v4, 0x3ffc, v4
	v_add_u32_e32 v4, 0x10200, v4
	ds_read_b32 v10, v4
	v_add_u32_e32 v4, 0xffffe810, v6
	v_and_b32_e32 v4, 0x3ffc, v4
	v_add_u32_e32 v4, 0x10200, v4
	ds_read_b32 v11, v4
	v_add_u32_e32 v4, 0xffffe010, v6
	v_and_b32_e32 v4, 0x3ffc, v4
	v_add_u32_e32 v4, 0x10200, v4
	ds_read_b32 v12, v4
	v_add_u32_e32 v4, 0xffffd810, v6
	v_and_b32_e32 v4, 0x3ffc, v4
	v_add_u32_e32 v4, 0x10200, v4
	ds_read_b32 v13, v4
	v_add_u32_e32 v4, 0xffffd010, v6
	v_and_b32_e32 v4, 0x3ffc, v4
	v_add_u32_e32 v4, 0x10200, v4
	ds_read_b32 v14, v4
	v_add_u32_e32 v4, 0xffffc810, v6
	v_and_b32_e32 v4, 0x3ffc, v4
	v_add_u32_e32 v4, 0x10200, v4
	ds_read_b32 v15, v4
	s_waitcnt lgkmcnt(8)
	v_mul_f32_e32 v16, v1, v16
	v_cvt_pk_bf16_f32 v16, v16, v155
	ds_write_b16 v2, v16 offset:24768
	v_mul_f32_e32 v17, v1, v17
	v_cvt_pk_bf16_f32 v17, v17, v155
	ds_write_b16 v2, v17 offset:25792
	v_mul_f32_e32 v18, v1, v18
	v_cvt_pk_bf16_f32 v18, v18, v155
	ds_write_b16 v2, v18 offset:26816
	v_mul_f32_e32 v19, v1, v19
	v_cvt_pk_bf16_f32 v19, v19, v155
	ds_write_b16 v2, v19 offset:27840
	v_mul_f32_e32 v20, v1, v20
	v_cvt_pk_bf16_f32 v20, v20, v155
	ds_write_b16 v2, v20 offset:28864
	v_mul_f32_e32 v21, v1, v21
	v_cvt_pk_bf16_f32 v21, v21, v155
	ds_write_b16 v2, v21 offset:29888
	v_mul_f32_e32 v22, v1, v22
	v_cvt_pk_bf16_f32 v22, v22, v155
	ds_write_b16 v2, v22 offset:30912
	v_mul_f32_e32 v23, v1, v23
	v_cvt_pk_bf16_f32 v23, v23, v155
	ds_write_b16 v2, v23 offset:31936
	v_add_u32_e32 v4, 0x14, v6
	v_and_b32_e32 v4, 0x3ffc, v4
	v_add_u32_e32 v4, 0x10200, v4
	ds_read_b32 v16, v4
	v_add_u32_e32 v4, 0xfffff814, v6
	v_and_b32_e32 v4, 0x3ffc, v4
	v_add_u32_e32 v4, 0x10200, v4
	ds_read_b32 v17, v4
	v_add_u32_e32 v4, 0xfffff014, v6
	v_and_b32_e32 v4, 0x3ffc, v4
	v_add_u32_e32 v4, 0x10200, v4
	ds_read_b32 v18, v4
	v_add_u32_e32 v4, 0xffffe814, v6
	v_and_b32_e32 v4, 0x3ffc, v4
	v_add_u32_e32 v4, 0x10200, v4
	ds_read_b32 v19, v4
	v_add_u32_e32 v4, 0xffffe014, v6
	v_and_b32_e32 v4, 0x3ffc, v4
	v_add_u32_e32 v4, 0x10200, v4
	ds_read_b32 v20, v4
	v_add_u32_e32 v4, 0xffffd814, v6
	v_and_b32_e32 v4, 0x3ffc, v4
	v_add_u32_e32 v4, 0x10200, v4
	ds_read_b32 v21, v4
	v_add_u32_e32 v4, 0xffffd014, v6
	v_and_b32_e32 v4, 0x3ffc, v4
	v_add_u32_e32 v4, 0x10200, v4
	ds_read_b32 v22, v4
	v_add_u32_e32 v4, 0xffffc814, v6
	v_and_b32_e32 v4, 0x3ffc, v4
	v_add_u32_e32 v4, 0x10200, v4
	ds_read_b32 v23, v4
	s_waitcnt lgkmcnt(8)
; #define LAS __attribute__((address_space(3)))
; __device__ __forceinline__ unsigned pk2(float lo, float hi) { unsigned r; asm("v_cvt_pk_bf16_f32 %0, %1, %2" : "=v"(r) : "v"(lo), "v"(hi)); return r; }
; __device__ __forceinline__ void hy_filter(const Args& a, int L, int order, int c, LAS unsigned char* lds) {
;     ...
;     const float inv = 1.0f / tot;
;     for (int i = tid; i < 8 * 4096; i += 512) {
;         const int q = i >> 12, x = i & 4095;
;         const float v = tmp[(q - x) & 4095] * inv;
;         *(LAS bf16_t*)(lds + q * HY_CP + x * 2) = (bf16_t)(pk2(v, 0.f) & 0xffffu);
;     }
	v_mul_f32_e32 v8, v1, v8
	v_cvt_pk_bf16_f32 v8, v8, v155
	ds_write_b16 v2, v8 offset:33024
	v_mul_f32_e32 v9, v1, v9
	v_cvt_pk_bf16_f32 v9, v9, v155
	ds_write_b16 v2, v9 offset:34048
	v_mul_f32_e32 v10, v1, v10
	v_cvt_pk_bf16_f32 v10, v10, v155
	ds_write_b16 v2, v10 offset:35072
	v_mul_f32_e32 v11, v1, v11
	v_cvt_pk_bf16_f32 v11, v11, v155
	ds_write_b16 v2, v11 offset:36096
	v_mul_f32_e32 v12, v1, v12
	v_cvt_pk_bf16_f32 v12, v12, v155
	ds_write_b16 v2, v12 offset:37120
	v_mul_f32_e32 v13, v1, v13
	v_cvt_pk_bf16_f32 v13, v13, v155
	ds_write_b16 v2, v13 offset:38144
	v_mul_f32_e32 v14, v1, v14
	v_cvt_pk_bf16_f32 v14, v14, v155
	ds_write_b16 v2, v14 offset:39168
	v_mul_f32_e32 v15, v1, v15
	v_cvt_pk_bf16_f32 v15, v15, v155
	ds_write_b16 v2, v15 offset:40192
	v_add_u32_e32 v4, 0x18, v6
	v_and_b32_e32 v4, 0x3ffc, v4
	v_add_u32_e32 v4, 0x10200, v4
	ds_read_b32 v8, v4
	v_add_u32_e32 v4, 0xfffff818, v6
	v_and_b32_e32 v4, 0x3ffc, v4
	v_add_u32_e32 v4, 0x10200, v4
	ds_read_b32 v9, v4
	v_add_u32_e32 v4, 0xfffff018, v6
	v_and_b32_e32 v4, 0x3ffc, v4
	v_add_u32_e32 v4, 0x10200, v4
	ds_read_b32 v10, v4
	v_add_u32_e32 v4, 0xffffe818, v6
	v_and_b32_e32 v4, 0x3ffc, v4
	v_add_u32_e32 v4, 0x10200, v4
	ds_read_b32 v11, v4
	v_add_u32_e32 v4, 0xffffe018, v6
	v_and_b32_e32 v4, 0x3ffc, v4
	v_add_u32_e32 v4, 0x10200, v4
	ds_read_b32 v12, v4
	v_add_u32_e32 v4, 0xffffd818, v6
	v_and_b32_e32 v4, 0x3ffc, v4
	v_add_u32_e32 v4, 0x10200, v4
	ds_read_b32 v13, v4
	v_add_u32_e32 v4, 0xffffd018, v6
	v_and_b32_e32 v4, 0x3ffc, v4
	v_add_u32_e32 v4, 0x10200, v4
	ds_read_b32 v14, v4
	v_add_u32_e32 v4, 0xffffc818, v6
	v_and_b32_e32 v4, 0x3ffc, v4
	v_add_u32_e32 v4, 0x10200, v4
	ds_read_b32 v15, v4
	s_waitcnt lgkmcnt(8)
	v_mul_f32_e32 v16, v1, v16
	v_cvt_pk_bf16_f32 v16, v16, v155
	ds_write_b16 v2, v16 offset:41280
	v_mul_f32_e32 v17, v1, v17
	v_cvt_pk_bf16_f32 v17, v17, v155
	ds_write_b16 v2, v17 offset:42304
	v_mul_f32_e32 v18, v1, v18
	v_cvt_pk_bf16_f32 v18, v18, v155
	ds_write_b16 v2, v18 offset:43328
	v_mul_f32_e32 v19, v1, v19
	v_cvt_pk_bf16_f32 v19, v19, v155
	ds_write_b16 v2, v19 offset:44352
	v_mul_f32_e32 v20, v1, v20
	v_cvt_pk_bf16_f32 v20, v20, v155
	ds_write_b16 v2, v20 offset:45376
	v_mul_f32_e32 v21, v1, v21
	v_cvt_pk_bf16_f32 v21, v21, v155
	ds_write_b16 v2, v21 offset:46400
	v_mul_f32_e32 v22, v1, v22
	v_cvt_pk_bf16_f32 v22, v22, v155
	ds_write_b16 v2, v22 offset:47424
	v_mul_f32_e32 v23, v1, v23
	v_cvt_pk_bf16_f32 v23, v23, v155
	ds_write_b16 v2, v23 offset:48448
	v_add_u32_e32 v4, 0x1c, v6
	v_and_b32_e32 v4, 0x3ffc, v4
	v_add_u32_e32 v4, 0x10200, v4
	ds_read_b32 v16, v4
	v_add_u32_e32 v4, 0xfffff81c, v6
	v_and_b32_e32 v4, 0x3ffc, v4
	v_add_u32_e32 v4, 0x10200, v4
	ds_read_b32 v17, v4
	v_add_u32_e32 v4, 0xfffff01c, v6
	v_and_b32_e32 v4, 0x3ffc, v4
	v_add_u32_e32 v4, 0x10200, v4
	ds_read_b32 v18, v4
	v_add_u32_e32 v4, 0xffffe81c, v6
	v_and_b32_e32 v4, 0x3ffc, v4
	v_add_u32_e32 v4, 0x10200, v4
	ds_read_b32 v19, v4
	v_add_u32_e32 v4, 0xffffe01c, v6
	v_and_b32_e32 v4, 0x3ffc, v4
	v_add_u32_e32 v4, 0x10200, v4
	ds_read_b32 v20, v4
	v_add_u32_e32 v4, 0xffffd81c, v6
	v_and_b32_e32 v4, 0x3ffc, v4
	v_add_u32_e32 v4, 0x10200, v4
	ds_read_b32 v21, v4
	v_add_u32_e32 v4, 0xffffd01c, v6
	v_and_b32_e32 v4, 0x3ffc, v4
	v_add_u32_e32 v4, 0x10200, v4
	ds_read_b32 v22, v4
	v_add_u32_e32 v4, 0xffffc81c, v6
	v_and_b32_e32 v4, 0x3ffc, v4
	v_add_u32_e32 v4, 0x10200, v4
	ds_read_b32 v23, v4
	s_waitcnt lgkmcnt(8)
	v_mul_f32_e32 v8, v1, v8
	v_cvt_pk_bf16_f32 v8, v8, v155
	ds_write_b16 v2, v8 offset:49536
	v_mul_f32_e32 v9, v1, v9
	v_cvt_pk_bf16_f32 v9, v9, v155
	ds_write_b16 v2, v9 offset:50560
	v_mul_f32_e32 v10, v1, v10
	v_cvt_pk_bf16_f32 v10, v10, v155
	ds_write_b16 v2, v10 offset:51584
	v_mul_f32_e32 v11, v1, v11
	v_cvt_pk_bf16_f32 v11, v11, v155
	ds_write_b16 v2, v11 offset:52608
	v_mul_f32_e32 v12, v1, v12
	v_cvt_pk_bf16_f32 v12, v12, v155
	ds_write_b16 v2, v12 offset:53632
	v_mul_f32_e32 v13, v1, v13
	v_cvt_pk_bf16_f32 v13, v13, v155
	ds_write_b16 v2, v13 offset:54656
	v_mul_f32_e32 v14, v1, v14
	v_cvt_pk_bf16_f32 v14, v14, v155
	ds_write_b16 v2, v14 offset:55680
	v_mul_f32_e32 v15, v1, v15
	v_cvt_pk_bf16_f32 v15, v15, v155
	ds_write_b16 v2, v15 offset:56704
	s_waitcnt lgkmcnt(0)
	v_mul_f32_e32 v16, v1, v16
	v_cvt_pk_bf16_f32 v16, v16, v155
	ds_write_b16 v2, v16 offset:57792
	v_mul_f32_e32 v17, v1, v17
	v_cvt_pk_bf16_f32 v17, v17, v155
	ds_write_b16 v2, v17 offset:58816
	v_mul_f32_e32 v18, v1, v18
	v_cvt_pk_bf16_f32 v18, v18, v155
	ds_write_b16 v2, v18 offset:59840
	v_mul_f32_e32 v19, v1, v19
	v_cvt_pk_bf16_f32 v19, v19, v155
	ds_write_b16 v2, v19 offset:60864
	v_mul_f32_e32 v20, v1, v20
	v_cvt_pk_bf16_f32 v20, v20, v155
	ds_write_b16 v2, v20 offset:61888
	v_mul_f32_e32 v21, v1, v21
	v_cvt_pk_bf16_f32 v21, v21, v155
	ds_write_b16 v2, v21 offset:62912
	v_mul_f32_e32 v22, v1, v22
	v_cvt_pk_bf16_f32 v22, v22, v155
	ds_write_b16 v2, v22 offset:63936
	v_mul_f32_e32 v23, v1, v23
	v_cvt_pk_bf16_f32 v23, v23, v155
	ds_write_b16 v2, v23 offset:64960
	v_add_u32_e32 v0, 0x8000, v0
	v_add_u32_e32 v2, 0x10000, v2
	v_add_u32_e32 v3, 0xffff8000, v3
	s_mov_b64 s[24:25], exec
